# GDN scan loop: 25 of the 44 per-step LDS fragment reads given their own registers and issued in batches of 12 with counted lgkmcnt waits, instead of read-wait-MFMA one at a time
# speedup vs baseline: 1.0028x; 1.0020x over previous
.LBB0_1067:
	s_bitcmp1_b32 s13, 0
	s_cselect_b32 s10, 0xe000, 0
	v_add_u32_e32 v170, s10, v168
	v_lshlrev_b32_e32 v80, 16, v68
	v_and_b32_e32 v81, 0xffff0000, v68
	v_lshlrev_b32_e32 v64, 16, v144
	v_and_b32_e32 v65, 0xffff0000, v144
	v_lshlrev_b32_e32 v82, 16, v69
	v_and_b32_e32 v83, 0xffff0000, v69
	v_lshlrev_b32_e32 v66, 16, v145
	v_and_b32_e32 v67, 0xffff0000, v145
	v_lshlrev_b32_e32 v84, 16, v70
	v_and_b32_e32 v85, 0xffff0000, v70
	v_lshlrev_b32_e32 v68, 16, v146
	v_and_b32_e32 v69, 0xffff0000, v146
	v_lshlrev_b32_e32 v86, 16, v71
	v_and_b32_e32 v87, 0xffff0000, v71
	v_lshlrev_b32_e32 v70, 16, v147
	v_and_b32_e32 v71, 0xffff0000, v147
	ds_read_b128 v[176:179], v170
	ds_read_b128 v[180:183], v170 offset:1024
	ds_read_b128 v[184:187], v170 offset:2048
	ds_read_b128 v[188:191], v170 offset:3072
	ds_read_b128 v[192:195], v170 offset:4096
	ds_read_b128 v[196:199], v170 offset:5120
	ds_read_b128 v[200:203], v170 offset:6144
	ds_read_b128 v[214:217], v170 offset:7168
	ds_read_b128 v[218:221], v170 offset:8192
	ds_read_b128 v[222:225], v170 offset:9216
	ds_read_b128 v[226:229], v170 offset:10240
	ds_read_b128 v[230:233], v170 offset:11264
	v_lshlrev_b32_e32 v88, 16, v92
	v_and_b32_e32 v89, 0xffff0000, v92
	v_lshlrev_b32_e32 v90, 16, v93
	v_and_b32_e32 v91, 0xffff0000, v93
	v_lshlrev_b32_e32 v92, 16, v94
	v_and_b32_e32 v93, 0xffff0000, v94
	v_lshlrev_b32_e32 v94, 16, v95
	v_and_b32_e32 v95, 0xffff0000, v95
	v_lshlrev_b32_e32 v72, 16, v76
	v_and_b32_e32 v73, 0xffff0000, v76
	s_waitcnt lgkmcnt(11)
	v_mfma_f32_32x32x16_bf16 v[80:95], v[176:179], v[112:115], v[80:95]
	v_lshlrev_b32_e32 v74, 16, v77
	v_and_b32_e32 v75, 0xffff0000, v77
	v_lshlrev_b32_e32 v76, 16, v78
	v_and_b32_e32 v77, 0xffff0000, v78
	v_lshlrev_b32_e32 v78, 16, v79
	v_and_b32_e32 v79, 0xffff0000, v79
	s_waitcnt lgkmcnt(10)
	v_mfma_f32_32x32x16_bf16 v[80:95], v[180:183], v[116:119], v[80:95]
	v_mul_f32_e64 v14, v14, v164
	v_mul_f32_e64 v15, v15, v164
	v_mul_f32_e64 v12, v12, v164
	v_mul_f32_e64 v13, v13, v164
	v_pk_mul_f32 v[10:11], v[10:11], v[164:165] op_sel_hi:[1,0]
	v_pk_mul_f32 v[8:9], v[8:9], v[164:165] op_sel_hi:[1,0]
	v_pk_mul_f32 v[6:7], v[6:7], v[164:165] op_sel_hi:[1,0]
	v_pk_mul_f32 v[4:5], v[4:5], v[164:165] op_sel_hi:[1,0]
	s_waitcnt lgkmcnt(9)
	v_mfma_f32_32x32x16_bf16 v[80:95], v[184:187], v[120:123], v[80:95]
	v_mul_f32_e64 v2, v2, v164
	v_mul_f32_e64 v3, v3, v164
	v_mul_f32_e64 v0, v0, v164
	v_mul_f32_e64 v1, v1, v164
	v_pk_mul_f32 v[30:31], v[30:31], v[164:165] op_sel_hi:[1,0]
	v_pk_mul_f32 v[28:29], v[28:29], v[164:165] op_sel_hi:[1,0]
	v_pk_mul_f32 v[26:27], v[26:27], v[164:165] op_sel_hi:[1,0]
	v_pk_mul_f32 v[24:25], v[24:25], v[164:165] op_sel_hi:[1,0]
	s_waitcnt lgkmcnt(8)
	v_mfma_f32_32x32x16_bf16 v[80:95], v[188:191], v[124:127], v[80:95]
	v_mul_f32_e64 v22, v22, v164
	v_mul_f32_e64 v23, v23, v164
	v_mul_f32_e64 v20, v20, v164
	v_mul_f32_e64 v21, v21, v164
	v_pk_mul_f32 v[18:19], v[18:19], v[164:165] op_sel_hi:[1,0]
	v_pk_mul_f32 v[16:17], v[16:17], v[164:165] op_sel_hi:[1,0]
	v_pk_mul_f32 v[46:47], v[46:47], v[164:165] op_sel_hi:[1,0]
	v_pk_mul_f32 v[44:45], v[44:45], v[164:165] op_sel_hi:[1,0]
	s_waitcnt lgkmcnt(7)
	v_mfma_f32_32x32x16_bf16 v[80:95], v[192:195], v[128:131], v[80:95]
	v_mul_f32_e64 v42, v42, v164
	v_mul_f32_e64 v43, v43, v164
	v_mul_f32_e64 v40, v40, v164
	v_mul_f32_e64 v41, v41, v164
	v_pk_mul_f32 v[38:39], v[38:39], v[164:165] op_sel_hi:[1,0]
	v_pk_mul_f32 v[36:37], v[36:37], v[164:165] op_sel_hi:[1,0]
	v_pk_mul_f32 v[34:35], v[34:35], v[164:165] op_sel_hi:[1,0]
	v_pk_mul_f32 v[32:33], v[32:33], v[164:165] op_sel_hi:[1,0]
	s_waitcnt lgkmcnt(6)
	v_mfma_f32_32x32x16_bf16 v[80:95], v[196:199], v[132:135], v[80:95]
	v_mul_f32_e64 v62, v62, v164
	v_mul_f32_e64 v63, v63, v164
	v_mul_f32_e64 v60, v60, v164
	v_mul_f32_e64 v61, v61, v164
	v_pk_mul_f32 v[58:59], v[58:59], v[164:165] op_sel_hi:[1,0]
	v_pk_mul_f32 v[56:57], v[56:57], v[164:165] op_sel_hi:[1,0]
	v_pk_mul_f32 v[54:55], v[54:55], v[164:165] op_sel_hi:[1,0]
	v_pk_mul_f32 v[52:53], v[52:53], v[164:165] op_sel_hi:[1,0]
	s_waitcnt lgkmcnt(5)
	v_mfma_f32_32x32x16_bf16 v[80:95], v[200:203], v[136:139], v[80:95]
	v_mul_f32_e64 v50, v50, v164
	v_mul_f32_e64 v51, v51, v164
	v_mul_f32_e64 v48, v48, v164
	v_mul_f32_e64 v49, v49, v164
	s_waitcnt lgkmcnt(4)
	v_mfma_f32_32x32x16_bf16 v[80:95], v[214:217], v[140:143], v[80:95]
	s_waitcnt lgkmcnt(3)
	v_mfma_f32_32x32x16_bf16 v[64:79], v[218:221], v[112:115], v[64:79]
	s_waitcnt lgkmcnt(2)
	v_mfma_f32_32x32x16_bf16 v[64:79], v[222:225], v[116:119], v[64:79]
	s_waitcnt lgkmcnt(1)
	v_mfma_f32_32x32x16_bf16 v[64:79], v[226:229], v[120:123], v[64:79]
	s_waitcnt lgkmcnt(0)
	v_mfma_f32_32x32x16_bf16 v[64:79], v[230:233], v[124:127], v[64:79]
	ds_read_b128 v[176:179], v170 offset:12288
	ds_read_b128 v[180:183], v170 offset:13312
	ds_read_b128 v[184:187], v170 offset:14336
	ds_read_b128 v[188:191], v170 offset:17408
	ds_read_b128 v[192:195], v170 offset:18432
	ds_read_b128 v[196:199], v170 offset:19456
	ds_read_b128 v[200:203], v170 offset:20480
	ds_read_b128 v[214:217], v170 offset:21504
	ds_read_b128 v[218:221], v170 offset:22528
	ds_read_b128 v[222:225], v170 offset:23552
	ds_read_b128 v[226:229], v170 offset:49152
	ds_read_b128 v[230:233], v170 offset:50176
	s_waitcnt lgkmcnt(11)
	v_mfma_f32_32x32x16_bf16 v[64:79], v[176:179], v[128:131], v[64:79]
	s_waitcnt lgkmcnt(10)
	v_mfma_f32_32x32x16_bf16 v[64:79], v[180:183], v[132:135], v[64:79]
	s_waitcnt lgkmcnt(9)
	v_mfma_f32_32x32x16_bf16 v[64:79], v[184:187], v[136:139], v[64:79]
	ds_read_b128 v[144:147], v170 offset:15360
	s_waitcnt lgkmcnt(0)
	v_mfma_f32_32x32x16_bf16 v[64:79], v[144:147], v[140:143], v[64:79]
	v_cvt_pk_bf16_f32 v144, v80, v81
	v_cvt_pk_bf16_f32 v145, v82, v83
	v_cvt_pk_bf16_f32 v146, v84, v85
	v_cvt_pk_bf16_f32 v147, v86, v87
	v_cvt_pk_bf16_f32 v80, v88, v89
	v_cvt_pk_bf16_f32 v81, v90, v91
	v_cvt_pk_bf16_f32 v82, v92, v93
	v_cvt_pk_bf16_f32 v83, v94, v95
	v_cvt_pk_bf16_f32 v88, v64, v65
	v_cvt_pk_bf16_f32 v89, v66, v67
	v_cvt_pk_bf16_f32 v90, v68, v69
	v_cvt_pk_bf16_f32 v91, v70, v71
	v_cvt_pk_bf16_f32 v84, v72, v73
	v_cvt_pk_bf16_f32 v85, v74, v75
	v_cvt_pk_bf16_f32 v86, v76, v77
	v_cvt_pk_bf16_f32 v87, v78, v79
	s_nop 11
	ds_read_b128 v[64:67], v170 offset:32768
	s_waitcnt lgkmcnt(0)
	v_mfma_f32_32x32x16_bf16 v[0:15], v[64:67], v[144:147], v[0:15]
	ds_read_b128 v[64:67], v170 offset:33792
	v_mov_b32_e32 v93, 0
	v_add_u32_e32 v92, s12, v149
	s_waitcnt lgkmcnt(0)
	v_mfma_f32_32x32x16_bf16 v[0:15], v[64:67], v[80:83], v[0:15]
	ds_read_b128 v[64:67], v170 offset:34816
	s_waitcnt lgkmcnt(0)
	v_mfma_f32_32x32x16_bf16 v[0:15], v[64:67], v[88:91], v[0:15]
	ds_read_b128 v[64:67], v170 offset:35840
	s_waitcnt lgkmcnt(0)
	v_mfma_f32_32x32x16_bf16 v[0:15], v[64:67], v[84:87], v[0:15]
	ds_read_b128 v[64:67], v170 offset:36864
	s_waitcnt lgkmcnt(0)
	v_mfma_f32_32x32x16_bf16 v[16:31], v[64:67], v[144:147], v[16:31]
	ds_read_b128 v[64:67], v170 offset:37888
	s_waitcnt lgkmcnt(0)
	v_mfma_f32_32x32x16_bf16 v[16:31], v[64:67], v[80:83], v[16:31]
	ds_read_b128 v[64:67], v170 offset:38912
	s_waitcnt lgkmcnt(0)
	v_mfma_f32_32x32x16_bf16 v[16:31], v[64:67], v[88:91], v[16:31]
	ds_read_b128 v[64:67], v170 offset:39936
	s_waitcnt lgkmcnt(0)
	v_mfma_f32_32x32x16_bf16 v[16:31], v[64:67], v[84:87], v[16:31]
	ds_read_b128 v[64:67], v170 offset:40960
	s_waitcnt lgkmcnt(0)
	v_mfma_f32_32x32x16_bf16 v[32:47], v[64:67], v[144:147], v[32:47]
	ds_read_b128 v[64:67], v170 offset:41984
	s_waitcnt lgkmcnt(0)
	v_mfma_f32_32x32x16_bf16 v[32:47], v[64:67], v[80:83], v[32:47]
	ds_read_b128 v[64:67], v170 offset:43008
	s_waitcnt lgkmcnt(0)
	v_mfma_f32_32x32x16_bf16 v[32:47], v[64:67], v[88:91], v[32:47]
	ds_read_b128 v[64:67], v170 offset:44032
	s_waitcnt lgkmcnt(0)
	v_mfma_f32_32x32x16_bf16 v[32:47], v[64:67], v[84:87], v[32:47]
	ds_read_b128 v[64:67], v170 offset:45056
	s_waitcnt lgkmcnt(0)
	v_mfma_f32_32x32x16_bf16 v[48:63], v[64:67], v[144:147], v[48:63]
	ds_read_b128 v[64:67], v170 offset:46080
	s_waitcnt lgkmcnt(0)
	v_mfma_f32_32x32x16_bf16 v[48:63], v[64:67], v[80:83], v[48:63]
	ds_read_b128 v[64:67], v170 offset:47104
	s_waitcnt lgkmcnt(0)
	v_mfma_f32_32x32x16_bf16 v[48:63], v[64:67], v[88:91], v[48:63]
	ds_read_b128 v[64:67], v170 offset:48128
	s_waitcnt lgkmcnt(0)
	v_mfma_f32_32x32x16_bf16 v[48:63], v[64:67], v[84:87], v[48:63]
	ds_read_b128 v[64:67], v170 offset:16384
	s_waitcnt lgkmcnt(0)
	v_mfma_f32_32x32x16_bf16 v[64:79], v[64:67], v[112:115], 0
	v_mfma_f32_32x32x16_bf16 v[64:79], v[188:191], v[116:119], v[64:79]
	s_waitcnt lgkmcnt(0)
	v_mfma_f32_32x32x16_bf16 v[64:79], v[192:195], v[120:123], v[64:79]
	s_waitcnt lgkmcnt(0)
	v_mfma_f32_32x32x16_bf16 v[64:79], v[196:199], v[124:127], v[64:79]
	s_waitcnt lgkmcnt(0)
	v_mfma_f32_32x32x16_bf16 v[64:79], v[200:203], v[128:131], v[64:79]
	s_waitcnt lgkmcnt(0)
	v_mfma_f32_32x32x16_bf16 v[64:79], v[214:217], v[132:135], v[64:79]
	s_waitcnt lgkmcnt(0)
	v_mfma_f32_32x32x16_bf16 v[64:79], v[218:221], v[136:139], v[64:79]
	s_waitcnt lgkmcnt(0)
	v_mfma_f32_32x32x16_bf16 v[64:79], v[222:225], v[140:143], v[64:79]
	s_waitcnt lgkmcnt(0)
	v_mfma_f32_32x32x16_bf16 v[64:79], v[226:229], v[144:147], v[64:79]
	s_waitcnt lgkmcnt(0)
	v_mfma_f32_32x32x16_bf16 v[64:79], v[230:233], v[80:83], v[64:79]
	ds_read_b128 v[176:179], v170 offset:51200
	s_waitcnt lgkmcnt(0)
	v_mfma_f32_32x32x16_bf16 v[64:79], v[176:179], v[88:91], v[64:79]
	ds_read_b128 v[172:175], v170 offset:52224
	s_waitcnt lgkmcnt(0)
	v_mfma_f32_32x32x16_bf16 v[64:79], v[172:175], v[84:87], v[64:79]
	s_nop 11
	v_mov_b32_dpp v93, v64 quad_perm:[1,0,3,2] row_mask:0xf bank_mask:0xf
	s_and_saveexec_b64 s[10:11], vcc
	s_cbranch_execz .LBB0_1069
	v_bfe_u32 v94, v64, 16, 1
	s_movk_i32 s14, 0x7fff
	v_add3_u32 v64, v64, v94, s14
	v_bfe_u32 v94, v93, 16, 1
	v_lshrrev_b32_e32 v64, 16, v64
	v_add3_u32 v93, v93, v94, s14
	s_mov_b32 s14, 0xffff0000
	v_and_or_b32 v64, v93, s14, v64
	s_movk_i32 s14, 0x600
	v_mad_i64_i32 v[94:95], s[14:15], v92, s14, v[150:151]
	global_store_dword v[94:95], v64, off
